# DSA run prologue: counted waits (vmcnt(12) before the mask build, vmcnt(8) before staging tile 0, vmcnt(0) before the pre-loop barrier) instead of one full drain
# baseline (speedup 1.0000x reference)
; #define LAS __attribute__((address_space(3)))
; #define LDS_WAIT() asm volatile("s_waitcnt lgkmcnt(0)" ::: "memory")
; __device__ __forceinline__ int t5_bucket(int rel) {
;     const int nabs = rel < 0 ? -rel : rel;
;     int bk = nabs;
;     if (nabs >= 8) bk = 8 + (nabs >= 12) + (nabs >= 16) + (nabs >= 23) + (nabs >= 32) + (nabs >= 46) + (nabs >= 64) + (nabs >= 91);
;     return bk + (rel > 0 ? 16 : 0);
; }
; __device__ __forceinline__ void dsa_unit(const bf16* QB, const int* SEL, bf16* AO, int b, int kvh, int t, LAS unsigned char* wl, int lane) {
;     const size_t rowbase = (size_t)b * SEQ, row = rowbase + t;
;     const int n = lane & 31, hi = lane >> 5, l15 = lane & 15, kq = lane >> 4;
;     const int ce = ((t >> 6) + 1) << 6; const int nsel = ce < 256 ? ce : 256;
;     LAS unsigned char* buf = wl;
;     LAS bf16* pT = (LAS bf16*)(wl + 9216);
;     LAS int* il = (LAS int*)(wl + 11264);
;     const LAS float* bl = (const LAS float*)(wl + 12288) + kvh * 128;
;     int sidx[8];
; #pragma unroll
;     for (int kb = 0; kb < 8; ++kb) { const int p = 32 * kb + n; sidx[kb] = (p < nsel) ? SEL[row * 256 + p] : 0; }
;     bf16x8 qf[4];
;     { const bf16* qp = QB + row * NBP + CQ + (kvh * 4 + (l15 & 3)) * 128 + 8 * kq;
; #pragma unroll
;       for (int ks = 0; ks < 4; ++ks) qf[ks] = *(const bf16x8*)(qp + 32 * ks); }
;     if (hi == 0) {
; #pragma unroll
;         for (int kb = 0; kb < 8; ++kb) il[32 * kb + n] = sidx[kb];
;     }
;     LDS_WAIT();
;     const int r4 = kq, c16 = l15;
;     const bf16* kg = QB + rowbase * NBP + CK + kvh * 128 + c16 * 8;
;     const bf16* vg = QB + rowbase * NBP + CV + kvh * 128 + c16 * 8;
;     bf16x8 kr[3][8];
; #pragma unroll
;     for (int pb = 0; pb < 3; ++pb)
; #pragma unroll
;         for (int i = 0; i < 8; ++i) kr[pb][i] = *(const bf16x8*)(kg + (size_t)il[32 * pb + 4 * i + r4] * NBP);
.Ldsa_selld_end:
	v_mov_b32_e32 v64, 0
	v_mov_b32_e32 v65, 0
	v_mov_b32_e32 v66, 0
	v_mov_b32_e32 v67, 0
	v_lshlrev_b32_e32 v179, 6, v206
	s_lshl_b32 s24, s0, 12
	s_add_u32 s24, s24, 0x11800
	v_add_u32_e32 v179, s24, v179
	ds_write_b128 v179, v[64:67] offset:0
	ds_write_b128 v179, v[64:67] offset:16
	ds_write_b128 v179, v[64:67] offset:32
	ds_write_b128 v179, v[64:67] offset:48
	v_lshrrev_b32_e32 v178, 4, v207
	v_add_u32_e32 v178, s4, v178
	v_and_b32_e32 v179, 15, v207
	v_lshlrev_b32_e32 v182, 4, v179
	s_lshl_b32 s24, s5, 8
	s_add_u32 s24, s24, 0x1000
	v_add_u32_e32 v182, s24, v182
	v_lshl_add_u64 v[160:161], s[78:79], 0, v[182:183]
	v_mad_u64_u32 v[160:161], s[12:13], v178, s23, v[160:161]
	s_mov_b32 s24, 0x44000
	s_mov_b32 s25, 0
	v_lshl_add_u64 v[162:163], v[160:161], 0, s[24:25]
	global_load_dwordx4 v[144:147], v[160:161], off
	global_load_dwordx4 v[148:151], v[160:161], off offset:1024
	global_load_dwordx4 v[152:155], v[162:163], off
	global_load_dwordx4 v[156:159], v[162:163], off offset:1024
	v_lshl_add_u64 v[160:161], v[160:161], 0, s[16:17]
	v_lshl_add_u64 v[162:163], v[162:163], 0, s[16:17]
	v_and_b32_e32 v64, 31, v206
	v_lshrrev_b32_e32 v65, 2, v64
	v_and_b32_e32 v66, 3, v64
	s_add_u32 s24, s44, s7
	s_add_u32 s24, s24, s4
	v_add_u32_e32 v178, s24, v65
	s_lshl_b32 s25, s5, 2
	v_add_u32_e32 v179, s25, v66
	v_lshlrev_b32_e32 v179, 8, v179
	v_lshl_add_u32 v182, v175, 1, v179
	v_lshl_add_u64 v[128:129], s[78:79], 0, v[182:183]
	v_mad_u64_u32 v[128:129], s[12:13], v178, s23, v[128:129]
	global_load_dwordx4 v[80:83], v[128:129], off offset:0
	global_load_dwordx4 v[84:87], v[128:129], off offset:32
	global_load_dwordx4 v[88:91], v[128:129], off offset:64
	global_load_dwordx4 v[92:95], v[128:129], off offset:96
	global_load_dwordx4 v[96:99], v[128:129], off offset:128
	global_load_dwordx4 v[100:103], v[128:129], off offset:160
	global_load_dwordx4 v[104:107], v[128:129], off offset:192
	global_load_dwordx4 v[108:111], v[128:129], off offset:224
	v_add_u32_e32 v178, s44, v65
	v_lshlrev_b32_e32 v172, 9, v178
	v_add_u32_e32 v172, 0x11800, v172
	s_add_u32 s24, s44, s7
	v_add_u32_e32 v178, s24, v65
	v_sub_u32_e32 v178, v175, v178
	v_add_u32_e32 v178, 0x80, v178
	v_lshlrev_b32_e32 v178, 2, v178
	v_lshl_add_u32 v177, v66, 10, v178
	v_add_u32_e32 v177, 0x1a400, v177
	s_sub_u32 s19, s24, 0x7a
	s_lshl_b32 s25, s5, 2
	v_add_u32_e32 v178, s25, v66
	v_lshlrev_b32_e32 v178, 7, v178
	v_add_u32_e32 v176, 0x1983c, v178
	ds_read_b32 v176, v176
	v_and_b32_e32 v64, 0xff, v207
	v_subrev_u32_e32 v65, 0x80, v64
	v_sub_u32_e32 v66, 0, v65
	v_max_i32_e32 v66, v65, v66
	v_mov_b32_e32 v67, 8
	v_cmp_le_i32_e32 vcc, 12, v66
	s_nop 1
	v_addc_co_u32_e32 v67, vcc, 0, v67, vcc
	v_cmp_le_i32_e32 vcc, 16, v66
	s_nop 1
	v_addc_co_u32_e32 v67, vcc, 0, v67, vcc
	v_cmp_le_i32_e32 vcc, 23, v66
	s_nop 1
	v_addc_co_u32_e32 v67, vcc, 0, v67, vcc
	v_cmp_le_i32_e32 vcc, 32, v66
	s_nop 1
	v_addc_co_u32_e32 v67, vcc, 0, v67, vcc
	v_cmp_le_i32_e32 vcc, 46, v66
	s_nop 1
	v_addc_co_u32_e32 v67, vcc, 0, v67, vcc
	v_cmp_le_i32_e32 vcc, 64, v66
	s_nop 1
	v_addc_co_u32_e32 v67, vcc, 0, v67, vcc
	v_cmp_le_i32_e32 vcc, 91, v66
	s_nop 1
	v_addc_co_u32_e32 v67, vcc, 0, v67, vcc
	v_cmp_gt_i32_e32 vcc, 8, v66
	s_nop 1
	v_cndmask_b32_e32 v67, v67, v66, vcc
	v_add_u32_e32 v68, 16, v67
	v_cmp_lt_i32_e32 vcc, 0, v65
	s_nop 1
	v_cndmask_b32_e32 v67, v67, v68, vcc
	v_lshrrev_b32_e32 v68, 8, v207
	s_lshl_b32 s24, s5, 2
	v_add_u32_e32 v69, s24, v68
	v_lshl_add_u32 v69, v69, 5, v67
	v_lshlrev_b32_e32 v69, 2, v69
	v_add_u32_e32 v69, 0x19800, v69
	ds_read_b32 v70, v69
	ds_read_b32 v71, v69 offset:256
	v_lshl_add_u32 v72, v68, 8, v64
	v_lshlrev_b32_e32 v72, 2, v72
	v_add_u32_e32 v72, 0x1a400, v72
	s_waitcnt lgkmcnt(0)
	ds_write_b32 v72, v70
	ds_write_b32 v72, v71 offset:2048
	s_waitcnt vmcnt(12)
	s_cmp_lg_u32 s0, 0
	s_cbranch_scc1 .Ldsa_f2
	v_mov_b32_e32 v132, 0x23c00
	s_mov_b64 exec, 1
	ds_write_b32 v132, v131
	s_mov_b64 exec, -1

; #define LAS __attribute__((address_space(3)))
; #define LDS_WAIT() asm volatile("s_waitcnt lgkmcnt(0)" ::: "memory")
; __device__ __forceinline__ void dsa_unit(const bf16* QB, const int* SEL, bf16* AO, int b, int kvh, int t, LAS unsigned char* wl, int lane) {
;     ...
;     bf16x8 kr[3][8];
; #pragma unroll
;     for (int pb = 0; pb < 3; ++pb)
; #pragma unroll
;         for (int i = 0; i < 8; ++i) kr[pb][i] = *(const bf16x8*)(kg + (size_t)il[32 * pb + 4 * i + r4] * NBP);
;     float lg[8][4];
;     float mx[4] = {-__builtin_inff(), -__builtin_inff(), -__builtin_inff(), -__builtin_inff()};
;     LAS unsigned char* kdst = buf + r4 * 272 + c16 * 16;
;     const LAS unsigned char* kfb = buf + l15 * 272 + 16 * kq;
;     const bool upper = (lane >> 4) & 1;
; #pragma unroll
;     for (int kb = 0; kb < 8; ++kb) {
; #pragma unroll
;         for (int i = 0; i < 8; ++i) *(LAS bf16x8*)(kdst + (4 * i) * 272) = kr[kb % 3][i];
;         if (kb + 3 < 8) {
; #pragma unroll
;             for (int i = 0; i < 8; ++i) kr[kb % 3][i] = *(const bf16x8*)(kg + (size_t)il[32 * (kb + 3) + 4 * i + r4] * NBP);
;         }
;         LDS_WAIT();
;         f32x4v a0 = {0.f, 0.f, 0.f, 0.f}, a1 = {0.f, 0.f, 0.f, 0.f};
; #pragma unroll
;         for (int ks = 0; ks < 4; ++ks) { const bf16x8 b0 = *(const LAS bf16x8*)(kfb + 64 * ks), b1 = *(const LAS bf16x8*)(kfb + 16 * 272 + 64 * ks);
;             a0 = __builtin_amdgcn_mfma_f32_16x16x32_bf16(qf[ks], b0, a0, 0, 0, 0); a1 = __builtin_amdgcn_mfma_f32_16x16x32_bf16(qf[ks], b1, a1, 0, 0, 0); }
;         LDS_WAIT();
;         const int bk = t5_bucket(sidx[kb] - t);
;         const bool valid = (32 * kb + n) < nsel;
; #pragma unroll
;         for (int g = 0; g < 4; ++g) { const float raw = upper ? a1[g] : a0[g]; const float v = valid ? raw + bl[g * 32 + bk] : -__builtin_inff(); lg[kb][g] = v; mx[g] = __builtin_fmaxf(mx[g], v); }
.Ldsa_selor_end:
	s_waitcnt vmcnt(8)
	ds_write_b128 v166, v[144:147]
	ds_write_b128 v167, v[148:151]
	ds_write_b128 v166, v[152:155] offset:8704
	ds_write_b128 v167, v[156:159] offset:9216
	v_mov_b32_e32 v0, 0
	v_mov_b32_e32 v1, 0
	v_mov_b32_e32 v2, 0
	v_mov_b32_e32 v3, 0
	v_mov_b32_e32 v4, 0
	v_mov_b32_e32 v5, 0
	v_mov_b32_e32 v6, 0
	v_mov_b32_e32 v7, 0
	v_mov_b32_e32 v8, 0
	v_mov_b32_e32 v9, 0
	v_mov_b32_e32 v10, 0
	v_mov_b32_e32 v11, 0
	v_mov_b32_e32 v12, 0
	v_mov_b32_e32 v13, 0
	v_mov_b32_e32 v14, 0
	v_mov_b32_e32 v15, 0
	v_mov_b32_e32 v16, 0
	v_mov_b32_e32 v17, 0
	v_mov_b32_e32 v18, 0
	v_mov_b32_e32 v19, 0
	v_mov_b32_e32 v20, 0
	v_mov_b32_e32 v21, 0
	v_mov_b32_e32 v22, 0
	v_mov_b32_e32 v23, 0
	v_mov_b32_e32 v24, 0
	v_mov_b32_e32 v25, 0
	v_mov_b32_e32 v26, 0
	v_mov_b32_e32 v27, 0
	v_mov_b32_e32 v28, 0
	v_mov_b32_e32 v29, 0
	v_mov_b32_e32 v30, 0
	v_mov_b32_e32 v31, 0
	v_mov_b32_e32 v32, 0
	v_mov_b32_e32 v33, 0
	v_mov_b32_e32 v34, 0
	v_mov_b32_e32 v35, 0
	v_mov_b32_e32 v36, 0
	v_mov_b32_e32 v37, 0
	v_mov_b32_e32 v38, 0
	v_mov_b32_e32 v39, 0
	v_mov_b32_e32 v40, 0
	v_mov_b32_e32 v41, 0
	v_mov_b32_e32 v42, 0
	v_mov_b32_e32 v43, 0
	v_mov_b32_e32 v44, 0
	v_mov_b32_e32 v45, 0
	v_mov_b32_e32 v46, 0
	v_mov_b32_e32 v47, 0
	v_mov_b32_e32 v48, 0
	v_mov_b32_e32 v49, 0
	v_mov_b32_e32 v50, 0
	v_mov_b32_e32 v51, 0
	v_mov_b32_e32 v52, 0
	v_mov_b32_e32 v53, 0
	v_mov_b32_e32 v54, 0
	v_mov_b32_e32 v55, 0
	v_mov_b32_e32 v56, 0
	v_mov_b32_e32 v57, 0
	v_mov_b32_e32 v58, 0
	v_mov_b32_e32 v59, 0
	v_mov_b32_e32 v60, 0
	v_mov_b32_e32 v61, 0
	v_mov_b32_e32 v62, 0
	v_mov_b32_e32 v63, 0
	v_mov_b32_e32 v173, 0
	s_mov_b32 s9, 0
	s_mov_b32 s10, 0
	s_mov_b32 s11, 0x8c00
	s_waitcnt vmcnt(0)
	s_waitcnt lgkmcnt(0)
	s_barrier
	s_mov_b32 s13, 0xf149f2ca
	ds_read_b32 v174, v172
	ds_read_b32 v182, v172 offset:4
	v_mov_b32_e32 v132, 0x23c00
	ds_read_b32 v131, v132
	s_waitcnt lgkmcnt(0)
	v_readfirstlane_b32 s35, v131
	v_lshrrev_b32_e32 v174, v175, v174
	v_bfe_i32 v178, v174, 0, 1
	v_bfi_b32 v64, v178, v176, s13
	v_bfe_i32 v179, v174, 1, 1
	v_bfi_b32 v65, v179, v176, s13
	v_bfe_i32 v178, v174, 2, 1
	v_bfi_b32 v66, v178, v176, s13
	v_bfe_i32 v179, v174, 3, 1
	v_bfi_b32 v67, v179, v176, s13
	v_bfe_i32 v178, v174, 4, 1
	v_bfi_b32 v68, v178, v176, s13
	v_bfe_i32 v179, v174, 5, 1
	v_bfi_b32 v69, v179, v176, s13
	v_bfe_i32 v178, v174, 6, 1
	v_bfi_b32 v70, v178, v176, s13
	v_bfe_i32 v179, v174, 7, 1
	v_bfi_b32 v71, v179, v176, s13
	v_bfe_i32 v178, v174, 16, 1
	v_bfi_b32 v72, v178, v176, s13
	v_bfe_i32 v179, v174, 17, 1
	v_bfi_b32 v73, v179, v176, s13
	v_bfe_i32 v178, v174, 18, 1
	v_bfi_b32 v74, v178, v176, s13
	v_bfe_i32 v179, v174, 19, 1
	v_bfi_b32 v75, v179, v176, s13
	v_bfe_i32 v178, v174, 20, 1
	v_bfi_b32 v76, v178, v176, s13
	v_bfe_i32 v179, v174, 21, 1
	v_bfi_b32 v77, v179, v176, s13
	v_bfe_i32 v178, v174, 22, 1
	v_bfi_b32 v78, v178, v176, s13
	v_bfe_i32 v179, v174, 23, 1
	v_bfi_b32 v79, v179, v176, s13
